# attention loop: K/V pointer increments moved from the serial tail to right after their loads (under the QK MFMAs)
# baseline (speedup 1.0000x reference)
.LBB0_1899:
	s_or_b64 exec, exec, s[2:3]
	v_pk_add_f32 v[80:81], v[96:97], v[80:81]
	v_pk_add_f32 v[64:65], v[64:65], v[112:113]
	v_add_f32_e32 v82, v98, v82
	v_add_f32_e32 v83, v246, v83
	v_pk_add_f32 v[66:67], v[66:67], v[114:115]
	v_pk_add_f32 v[84:85], v[100:101], v[84:85]
	v_pk_add_f32 v[68:69], v[68:69], v[116:117]
	v_pk_add_f32 v[86:87], v[102:103], v[86:87]
	v_pk_add_f32 v[70:71], v[70:71], v[118:119]
	v_pk_add_f32 v[88:89], v[104:105], v[88:89]
	v_pk_add_f32 v[72:73], v[72:73], v[120:121]
	v_pk_add_f32 v[90:91], v[106:107], v[90:91]
	v_pk_add_f32 v[74:75], v[74:75], v[122:123]
	v_pk_add_f32 v[92:93], v[108:109], v[92:93]
	v_pk_add_f32 v[76:77], v[76:77], v[124:125]
	v_pk_add_f32 v[94:95], v[110:111], v[94:95]
	v_add_f32_e32 v78, v78, v126
	v_add_f32_e32 v79, v79, v99
	v_pk_add_f32 v[80:81], v[80:81], v[82:83]
	v_pk_add_f32 v[64:65], v[64:65], v[66:67]
	v_pk_add_f32 v[84:85], v[84:85], v[86:87]
	v_pk_add_f32 v[68:69], v[68:69], v[70:71]
	v_pk_add_f32 v[88:89], v[88:89], v[90:91]
	v_pk_add_f32 v[72:73], v[72:73], v[74:75]
	v_pk_add_f32 v[92:93], v[92:93], v[94:95]
	v_pk_add_f32 v[76:77], v[76:77], v[78:79]
	v_pk_add_f32 v[80:81], v[80:81], v[84:85]
	v_pk_add_f32 v[64:65], v[64:65], v[68:69]
	v_pk_add_f32 v[88:89], v[88:89], v[92:93]
	v_pk_add_f32 v[72:73], v[72:73], v[76:77]
	v_pk_add_f32 v[80:81], v[80:81], v[88:89]
	v_pk_add_f32 v[64:65], v[64:65], v[72:73]
	v_add_f32_e32 v80, v80, v81
	v_add_f32_e32 v64, v64, v65
	s_add_i32 s8, s8, 1
	v_add_f32_e32 v131, v131, v80
	v_add_f32_e32 v193, v193, v64
	v_add3_u32 v64, s9, v244, v128
	s_cmpk_eq_i32 s8, 0x84
	ds_write_b128 v64, v[188:191] offset:13312
	s_waitcnt lgkmcnt(0)
	s_barrier
	s_cbranch_scc1 .LBB0_1908
.LBB0_1900:
	global_load_dwordx4 v[184:187], v[216:217], off
	v_lshl_add_u64 v[216:217], v[216:217], 0, s[16:17]
	s_and_saveexec_b64 s[2:3], s[42:43]
	s_cbranch_execz .LBB0_1902
	global_load_dwordx4 v[180:183], v[214:215], off
.LBB0_1902:
	s_or_b64 exec, exec, s[2:3]
	v_lshl_add_u64 v[214:215], v[214:215], 0, s[16:17]
	s_and_b32 s2, 1, s8
	s_cselect_b32 s3, 0, 0x5800
	s_add_i32 s3, s3, 0
	v_add3_u32 v92, s3, v245, v210
	ds_read_b128 v[80:83], v92
	ds_read_b128 v[84:87], v92 offset:32
	ds_read_b128 v[88:91], v92 offset:6656
	ds_read_b128 v[188:191], v92 offset:6688
	s_waitcnt lgkmcnt(0)
	v_mfma_f32_32x32x16_bf16 v[112:127], v[80:83], v[176:179], 0
	v_mfma_f32_32x32x16_bf16 v[96:111], v[80:83], v[152:155], 0
	v_mfma_f32_32x32x16_bf16 v[112:127], v[84:87], v[172:175], v[112:127]
	v_mfma_f32_32x32x16_bf16 v[96:111], v[84:87], v[148:151], v[96:111]
	ds_read_b128 v[80:83], v92 offset:64
	ds_read_b128 v[84:87], v92 offset:96
	ds_read_b128 v[194:197], v92 offset:6720
	ds_read_b128 v[246:249], v92 offset:6752
	s_waitcnt lgkmcnt(0)
	v_mfma_f32_32x32x16_bf16 v[112:127], v[80:83], v[168:171], v[112:127]
	v_mfma_f32_32x32x16_bf16 v[96:111], v[80:83], v[144:147], v[96:111]
	v_mfma_f32_32x32x16_bf16 v[112:127], v[84:87], v[164:167], v[112:127]
	v_mfma_f32_32x32x16_bf16 v[96:111], v[84:87], v[140:143], v[96:111]
	ds_read_b128 v[80:83], v92 offset:128
	ds_read_b128 v[84:87], v92 offset:160
	ds_read_b128 v[200:203], v92 offset:6784
	ds_read_b128 v[224:227], v92 offset:6816
	s_waitcnt lgkmcnt(0)
	v_mfma_f32_32x32x16_bf16 v[112:127], v[80:83], v[160:163], v[112:127]
	v_mfma_f32_32x32x16_bf16 v[96:111], v[80:83], v[136:139], v[96:111]
	v_mfma_f32_32x32x16_bf16 v[64:79], v[88:91], v[176:179], 0
	v_mfma_f32_32x32x16_bf16 v[112:127], v[84:87], v[156:159], v[112:127]
	v_mfma_f32_32x32x16_bf16 v[96:111], v[84:87], v[132:135], v[96:111]
	s_nop 10
	v_mfma_f32_32x32x16_bf16 v[80:95], v[88:91], v[152:155], 0
	v_mfma_f32_32x32x16_bf16 v[64:79], v[188:191], v[172:175], v[64:79]
	v_mfma_f32_32x32x16_bf16 v[80:95], v[188:191], v[148:151], v[80:95]
	global_load_dwordx4 v[188:191], v[212:213], off
	v_lshl_add_u64 v[212:213], v[212:213], 0, s[24:25]
	v_mfma_f32_32x32x16_bf16 v[64:79], v[194:197], v[168:171], v[64:79]
	v_mfma_f32_32x32x16_bf16 v[64:79], v[246:249], v[164:167], v[64:79]
	v_mfma_f32_32x32x16_bf16 v[64:79], v[200:203], v[160:163], v[64:79]
	v_mfma_f32_32x32x16_bf16 v[80:95], v[194:197], v[144:147], v[80:95]
	v_mfma_f32_32x32x16_bf16 v[64:79], v[224:227], v[156:159], v[64:79]
	v_mfma_f32_32x32x16_bf16 v[80:95], v[246:249], v[140:143], v[80:95]
	s_nop 10
	v_max_f32_e32 v218, v112, v64
	v_max3_f32 v218, v218, v113, v65
	v_max3_f32 v218, v218, v114, v66
	v_max3_f32 v194, v218, v115, v67
	v_max3_f32 v194, v194, v116, v68
	v_max3_f32 v194, v194, v117, v69
	v_mfma_f32_32x32x16_bf16 v[80:95], v[200:203], v[136:139], v[80:95]
	v_max3_f32 v194, v194, v118, v70
	v_max3_f32 v194, v194, v119, v71
	v_max3_f32 v194, v194, v120, v72
	v_max3_f32 v194, v194, v121, v73
	v_max3_f32 v194, v194, v122, v74
	v_max3_f32 v194, v194, v123, v75
	v_max3_f32 v194, v194, v124, v76
	v_max3_f32 v194, v194, v125, v77
	v_mfma_f32_32x32x16_bf16 v[80:95], v[224:227], v[132:135], v[80:95]
	v_max3_f32 v194, v194, v126, v78
	v_max3_f32 v194, v194, v127, v79
	v_mov_b32_e32 v195, v194
	s_nop 1
	v_permlane32_swap_b32_e32 v194, v195
	v_max_f32_e32 v246, v194, v195
	v_add_f32_e32 v194, 0x41000000, v239
	v_cmp_gt_f32_e32 vcc, v246, v194
	s_cbranch_vccz .LBB0_1904
	v_max_f32_e32 v194, v246, v246
	v_max_f32_e32 v195, v239, v239
	v_max_f32_e32 v195, v195, v194
	v_sub_f32_e32 v194, v239, v195
	v_exp_f32_e32 v194, v194
	v_mov_b32_e32 v239, v195
	v_pk_mul_f32 v[46:47], v[46:47], v[194:195] op_sel_hi:[1,0]
	v_pk_mul_f32 v[44:45], v[44:45], v[194:195] op_sel_hi:[1,0]
	v_pk_mul_f32 v[42:43], v[42:43], v[194:195] op_sel_hi:[1,0]
	v_pk_mul_f32 v[40:41], v[40:41], v[194:195] op_sel_hi:[1,0]
	v_pk_mul_f32 v[38:39], v[38:39], v[194:195] op_sel_hi:[1,0]
	v_pk_mul_f32 v[36:37], v[36:37], v[194:195] op_sel_hi:[1,0]
	v_pk_mul_f32 v[34:35], v[34:35], v[194:195] op_sel_hi:[1,0]
	v_pk_mul_f32 v[32:33], v[32:33], v[194:195] op_sel_hi:[1,0]
	v_pk_mul_f32 v[62:63], v[62:63], v[194:195] op_sel_hi:[1,0]
	v_pk_mul_f32 v[60:61], v[60:61], v[194:195] op_sel_hi:[1,0]
	v_pk_mul_f32 v[58:59], v[58:59], v[194:195] op_sel_hi:[1,0]
	v_pk_mul_f32 v[56:57], v[56:57], v[194:195] op_sel_hi:[1,0]
	v_pk_mul_f32 v[54:55], v[54:55], v[194:195] op_sel_hi:[1,0]
	v_pk_mul_f32 v[52:53], v[52:53], v[194:195] op_sel_hi:[1,0]
	v_pk_mul_f32 v[50:51], v[50:51], v[194:195] op_sel_hi:[1,0]
	v_pk_mul_f32 v[48:49], v[48:49], v[194:195] op_sel_hi:[1,0]
	v_mul_f32_e32 v193, v193, v194
